# v40 plus first four exps of each attention step moved from PV phase head to the end of the QK phase
# speedup vs baseline: 1.0109x; 1.0109x over previous
; #define WAIT_BAR(N) asm volatile("s_waitcnt vmcnt(" #N ") lgkmcnt(0)\n\ts_barrier":::"memory")
;   #define RESC() do{ if(resc){ asm volatile("s_waitcnt lgkmcnt(0)":::"memory"); \
;       _Pragma("unroll") for(int d_=0;d_<2;++d_) _Pragma("unroll") for(int r=0;r<16;++r)o[d_][r]*=wsf[crow(r,hi)]; } }while(0)
;   #define ROT() do{sl_prev=sl_cur;sl_cur=sl_next;sl_next=(sl_next==(NSLOT-1)*SLOTB)?0:sl_next+SLOTB;}while(0)
; template<int THRL> __device__ __forceinline__ void attn_unit(const bf16*Qu,const bf16*__restrict__ Kh,const bf16*__restrict__ Vh,bf16*Ou,const int NT,const float shift,char*shm){
;     ...
;   int t=1;
;     ...
;   for(;t+5<NT;t+=2){
;     STEP(pB0,pB1,pA0,pA1,t,true,true,true);     WAIT_BAR(2); RESC(); ROT();
.LBB0_618:
	s_mov_b32 s4, s76
	s_mov_b32 s5, s26
	s_mov_b32 s25, s31
	ds_read_b64_tr_b16 v[52:53], v51 offset:24576
	ds_read_b64_tr_b16 v[54:55], v51 offset:25088
	s_waitcnt lgkmcnt(9)
	v_mfma_f32_32x32x16_bf16 v[114:129], v[190:193], v[150:153], v[34:49]
	v_add_f32_e32 v50, v82, v50
	v_add_f32_e32 v194, v83, v194
	v_add_f32_e32 v195, v84, v195
	v_add_f32_e32 v196, v85, v196
	v_add_f32_e32 v50, v86, v50
	v_add_f32_e32 v194, v87, v194
	v_cvt_pk_bf16_f32 v158, v82, v83
	v_cvt_pk_bf16_f32 v159, v84, v85
	ds_read_b64_tr_b16 v[60:61], v51 offset:28672
	ds_read_b64_tr_b16 v[62:63], v51 offset:29184
	s_waitcnt lgkmcnt(10)
	v_mfma_f32_32x32x16_bf16 v[98:113], v[186:189], v[150:153], v[34:49]
	v_add_f32_e32 v195, v88, v195
	v_add_f32_e32 v196, v89, v196
	v_add_f32_e32 v50, v90, v50
	v_add_f32_e32 v194, v91, v194
	v_cvt_pk_bf16_f32 v160, v86, v87
	v_cvt_pk_bf16_f32 v161, v88, v89
	ds_read_b64_tr_b16 v[82:83], v51 offset:25600
	ds_read_b64_tr_b16 v[84:85], v51 offset:26112
	s_waitcnt lgkmcnt(11)
	v_mfma_f32_32x32x16_bf16 v[114:129], v[182:185], v[138:141], v[114:129]
	v_add_f32_e32 v195, v92, v195
	v_add_f32_e32 v196, v93, v196
	v_add_f32_e32 v50, v94, v50
	v_add_f32_e32 v194, v95, v194
	v_cvt_pk_bf16_f32 v154, v90, v91
	v_cvt_pk_bf16_f32 v155, v92, v93
	ds_read_b64_tr_b16 v[86:87], v51 offset:29696
	ds_read_b64_tr_b16 v[88:89], v51 offset:30208
	s_waitcnt lgkmcnt(12)
	v_mfma_f32_32x32x16_bf16 v[98:113], v[178:181], v[138:141], v[98:113]
	v_add_f32_e32 v195, v96, v195
	v_add_f32_e32 v196, v97, v196
	v_add_f32_e32 v50, v66, v50
	v_add_f32_e32 v194, v67, v194
	v_cvt_pk_bf16_f32 v156, v94, v95
	v_cvt_pk_bf16_f32 v157, v96, v97
	ds_read_b64_tr_b16 v[90:91], v51 offset:26624
	ds_read_b64_tr_b16 v[92:93], v51 offset:27136
	s_waitcnt lgkmcnt(13)
	v_mfma_f32_32x32x16_bf16 v[114:129], v[174:177], v[134:137], v[114:129]
	v_add_f32_e32 v195, v68, v195
	v_add_f32_e32 v196, v69, v196
	v_add_f32_e32 v50, v70, v50
	v_add_f32_e32 v194, v71, v194
	v_cvt_pk_bf16_f32 v146, v66, v67
	v_cvt_pk_bf16_f32 v147, v68, v69
	ds_read_b64_tr_b16 v[64:65], v51 offset:30720
	ds_read_b64_tr_b16 v[66:67], v51 offset:31232
	s_waitcnt lgkmcnt(14)
	v_mfma_f32_32x32x16_bf16 v[98:113], v[170:173], v[134:137], v[98:113]
	v_add_f32_e32 v195, v72, v195
	v_add_f32_e32 v196, v73, v196
	v_add_f32_e32 v50, v74, v50
	v_add_f32_e32 v194, v75, v194
	v_cvt_pk_bf16_f32 v148, v70, v71
	v_cvt_pk_bf16_f32 v149, v72, v73
	ds_read_b64_tr_b16 v[68:69], v51 offset:27648
	ds_read_b64_tr_b16 v[70:71], v51 offset:28160
	s_waitcnt lgkmcnt(14)
	v_mfma_f32_32x32x16_bf16 v[114:129], v[166:169], v[130:133], v[114:129]
	v_add_f32_e32 v195, v76, v195
	v_add_f32_e32 v196, v77, v196
	v_add_f32_e32 v50, v78, v50
	v_add_f32_e32 v194, v79, v194
	v_cvt_pk_bf16_f32 v142, v74, v75
	v_cvt_pk_bf16_f32 v143, v76, v77
	ds_read_b64_tr_b16 v[72:73], v51 offset:31744
	ds_read_b64_tr_b16 v[74:75], v51 offset:32256
	v_mfma_f32_32x32x16_bf16 v[98:113], v[162:165], v[130:133], v[98:113]
	v_add_f32_e32 v195, v80, v195
	v_add_f32_e32 v196, v81, v196
	v_cvt_pk_bf16_f32 v144, v78, v79
	v_cvt_pk_bf16_f32 v145, v80, v81
	v_exp_f32_e32 v114, v114
	v_exp_f32_e32 v115, v115
	v_exp_f32_e32 v116, v116
	v_exp_f32_e32 v117, v117
	s_add_i32 s6, s31, s70
	s_mov_b32 s7, m0
	s_mov_b32 m0, s6
	s_nop 0
	global_load_lds_dwordx4 v197, s[98:99]
	s_mov_b32 m0, s7
	s_add_i32 s6, s76, s71
	s_mov_b32 s7, m0
	s_mov_b32 m0, s6
	s_nop 0
	global_load_lds_dwordx4 v197, s[100:101]
	s_mov_b32 m0, s7
	s_add_u32 s98, s98, 0x2000
	s_addc_u32 s99, s99, 0
	s_add_u32 s100, s100, 0x2000
	s_addc_u32 s101, s101, 0
	s_waitcnt lgkmcnt(14)
	v_mfma_f32_32x32x16_bf16 v[2:17], v[158:161], v[52:55], v[2:17]
	s_waitcnt lgkmcnt(12)
	v_mfma_f32_32x32x16_bf16 v[18:33], v[158:161], v[60:63], v[18:33]
	v_exp_f32_e32 v118, v118
	v_exp_f32_e32 v119, v119
	v_exp_f32_e32 v120, v120
	v_exp_f32_e32 v121, v121
	v_add_u32_e32 v52, s4, v244
	v_add_u32_e32 v198, s25, v245
	ds_read_b128 v[60:63], v52
	ds_read_b128 v[162:165], v52 offset:512
	s_waitcnt lgkmcnt(12)
	v_mfma_f32_32x32x16_bf16 v[2:17], v[154:157], v[82:85], v[2:17]
	v_exp_f32_e32 v122, v122
	v_exp_f32_e32 v123, v123
	v_exp_f32_e32 v124, v124
	v_exp_f32_e32 v125, v125
	ds_read_b128 v[166:169], v52 offset:2048
	ds_read_b128 v[170:173], v52 offset:2560
	s_waitcnt lgkmcnt(12)
	v_mfma_f32_32x32x16_bf16 v[18:33], v[154:157], v[86:89], v[18:33]
	v_exp_f32_e32 v126, v126
	v_exp_f32_e32 v127, v127
	v_exp_f32_e32 v128, v128
	v_exp_f32_e32 v129, v129
	ds_read_b128 v[174:177], v52 offset:4096
	ds_read_b128 v[178:181], v52 offset:4608
	s_waitcnt lgkmcnt(12)
	v_mfma_f32_32x32x16_bf16 v[2:17], v[146:149], v[90:93], v[2:17]
	v_exp_f32_e32 v98, v98
	v_exp_f32_e32 v99, v99
	v_exp_f32_e32 v100, v100
	v_exp_f32_e32 v101, v101
	ds_read_b128 v[182:185], v52 offset:6144
	ds_read_b128 v[52:55], v52 offset:6656
	s_waitcnt lgkmcnt(12)
	v_mfma_f32_32x32x16_bf16 v[18:33], v[146:149], v[64:67], v[18:33]
	v_exp_f32_e32 v102, v102
	v_exp_f32_e32 v103, v103
	v_exp_f32_e32 v104, v104
	v_exp_f32_e32 v105, v105
	s_waitcnt lgkmcnt(10)
	v_mfma_f32_32x32x16_bf16 v[2:17], v[142:145], v[68:71], v[2:17]
	v_exp_f32_e32 v106, v106
	v_exp_f32_e32 v107, v107
	v_exp_f32_e32 v108, v108
	v_exp_f32_e32 v109, v109
	s_waitcnt lgkmcnt(8)
	v_mfma_f32_32x32x16_bf16 v[18:33], v[142:145], v[72:75], v[18:33]
	v_exp_f32_e32 v110, v110
	v_exp_f32_e32 v111, v111
	v_exp_f32_e32 v112, v112
	v_exp_f32_e32 v113, v113
	s_waitcnt vmcnt(2) lgkmcnt(0)
	s_barrier
; #define WAIT_BAR(N) asm volatile("s_waitcnt vmcnt(" #N ") lgkmcnt(0)\n\ts_barrier":::"memory")
;   #define RESC() do{ if(resc){ asm volatile("s_waitcnt lgkmcnt(0)":::"memory"); \
;       _Pragma("unroll") for(int d_=0;d_<2;++d_) _Pragma("unroll") for(int r=0;r<16;++r)o[d_][r]*=wsf[crow(r,hi)]; } }while(0)
;   #define ROT() do{sl_prev=sl_cur;sl_cur=sl_next;sl_next=(sl_next==(NSLOT-1)*SLOTB)?0:sl_next+SLOTB;}while(0)
; template<int THRL> __device__ __forceinline__ void attn_unit(const bf16*Qu,const bf16*__restrict__ Kh,const bf16*__restrict__ Vh,bf16*Ou,const int NT,const float shift,char*shm){
;     ...
;   int t=1;
;     ...
;   for(;t+5<NT;t+=2){
;     STEP(pB0,pB1,pA0,pA1,t,true,true,true);     WAIT_BAR(2); RESC(); ROT();
	s_add_i32 s6, s76, 0x2000
	s_cmpk_lg_i32 s76, 0x4000
	s_cselect_b32 s31, s6, 0
	ds_read_b64_tr_b16 v[186:187], v198 offset:24576
	ds_read_b64_tr_b16 v[188:189], v198 offset:25088
	s_waitcnt lgkmcnt(9)
	v_mfma_f32_32x32x16_bf16 v[82:97], v[60:63], v[150:153], v[34:49]
	v_add_f32_e32 v50, v114, v50
	v_add_f32_e32 v194, v115, v194
	v_add_f32_e32 v195, v116, v195
	v_add_f32_e32 v196, v117, v196
	v_add_f32_e32 v50, v118, v50
	v_add_f32_e32 v194, v119, v194
	v_cvt_pk_bf16_f32 v158, v114, v115
	v_cvt_pk_bf16_f32 v159, v116, v117
	ds_read_b64_tr_b16 v[60:61], v198 offset:28672
	ds_read_b64_tr_b16 v[62:63], v198 offset:29184
	s_waitcnt lgkmcnt(10)
	v_mfma_f32_32x32x16_bf16 v[66:81], v[162:165], v[150:153], v[34:49]
	v_add_f32_e32 v195, v120, v195
	v_add_f32_e32 v196, v121, v196
	v_add_f32_e32 v50, v122, v50
	v_add_f32_e32 v194, v123, v194
	v_cvt_pk_bf16_f32 v160, v118, v119
	v_cvt_pk_bf16_f32 v161, v120, v121
	ds_read_b64_tr_b16 v[114:115], v198 offset:25600
	ds_read_b64_tr_b16 v[116:117], v198 offset:26112
	s_waitcnt lgkmcnt(11)
	v_mfma_f32_32x32x16_bf16 v[82:97], v[166:169], v[138:141], v[82:97]
	v_add_f32_e32 v195, v124, v195
	v_add_f32_e32 v196, v125, v196
	v_add_f32_e32 v50, v126, v50
	v_add_f32_e32 v194, v127, v194
	v_cvt_pk_bf16_f32 v154, v122, v123
	v_cvt_pk_bf16_f32 v155, v124, v125
	ds_read_b64_tr_b16 v[118:119], v198 offset:29696
	ds_read_b64_tr_b16 v[120:121], v198 offset:30208
	s_waitcnt lgkmcnt(12)
	v_mfma_f32_32x32x16_bf16 v[66:81], v[170:173], v[138:141], v[66:81]
	v_add_f32_e32 v195, v128, v195
	v_add_f32_e32 v196, v129, v196
	v_add_f32_e32 v50, v98, v50
	v_add_f32_e32 v194, v99, v194
	v_cvt_pk_bf16_f32 v156, v126, v127
	v_cvt_pk_bf16_f32 v157, v128, v129
	ds_read_b64_tr_b16 v[122:123], v198 offset:26624
	ds_read_b64_tr_b16 v[124:125], v198 offset:27136
	s_waitcnt lgkmcnt(13)
	v_mfma_f32_32x32x16_bf16 v[82:97], v[174:177], v[134:137], v[82:97]
	v_add_f32_e32 v195, v100, v195
	v_add_f32_e32 v196, v101, v196
	v_add_f32_e32 v50, v102, v50
	v_add_f32_e32 v194, v103, v194
	v_cvt_pk_bf16_f32 v146, v98, v99
	v_cvt_pk_bf16_f32 v147, v100, v101
	ds_read_b64_tr_b16 v[98:99], v198 offset:30720
	ds_read_b64_tr_b16 v[100:101], v198 offset:31232
	s_waitcnt lgkmcnt(14)
	v_mfma_f32_32x32x16_bf16 v[66:81], v[178:181], v[134:137], v[66:81]
	v_add_f32_e32 v195, v104, v195
	v_add_f32_e32 v196, v105, v196
	v_add_f32_e32 v50, v106, v50
	v_add_f32_e32 v194, v107, v194
	v_cvt_pk_bf16_f32 v148, v102, v103
	v_cvt_pk_bf16_f32 v149, v104, v105
	ds_read_b64_tr_b16 v[102:103], v198 offset:27648
	ds_read_b64_tr_b16 v[104:105], v198 offset:28160
	s_waitcnt lgkmcnt(14)
	v_mfma_f32_32x32x16_bf16 v[82:97], v[182:185], v[130:133], v[82:97]
	v_add_f32_e32 v195, v108, v195
	v_add_f32_e32 v196, v109, v196
	v_add_f32_e32 v50, v110, v50
	v_add_f32_e32 v194, v111, v194
	v_cvt_pk_bf16_f32 v142, v106, v107
	v_cvt_pk_bf16_f32 v143, v108, v109
	ds_read_b64_tr_b16 v[106:107], v198 offset:31744
	ds_read_b64_tr_b16 v[108:109], v198 offset:32256
	v_mfma_f32_32x32x16_bf16 v[66:81], v[52:55], v[130:133], v[66:81]
	v_add_f32_e32 v195, v112, v195
	v_add_f32_e32 v196, v113, v196
	v_cvt_pk_bf16_f32 v144, v110, v111
	v_cvt_pk_bf16_f32 v145, v112, v113
	v_exp_f32_e32 v82, v82
	v_exp_f32_e32 v83, v83
	v_exp_f32_e32 v84, v84
	v_exp_f32_e32 v85, v85
	s_add_i32 s6, s76, s70
	s_mov_b32 s7, m0
	s_mov_b32 m0, s6
	s_nop 0
	global_load_lds_dwordx4 v197, s[98:99]
	s_mov_b32 m0, s7
	s_add_i32 s6, s31, s71
	s_mov_b32 s7, m0
	s_mov_b32 m0, s6
	s_nop 0
	global_load_lds_dwordx4 v197, s[100:101]
	s_mov_b32 m0, s7
	s_add_u32 s98, s98, 0x2000
	s_addc_u32 s99, s99, 0
	s_add_u32 s100, s100, 0x2000
	s_addc_u32 s101, s101, 0
	s_waitcnt lgkmcnt(14)
	v_mfma_f32_32x32x16_bf16 v[2:17], v[158:161], v[186:189], v[2:17]
	s_waitcnt lgkmcnt(12)
	v_mfma_f32_32x32x16_bf16 v[18:33], v[158:161], v[60:63], v[18:33]
	v_exp_f32_e32 v86, v86
	v_exp_f32_e32 v87, v87
	v_exp_f32_e32 v88, v88
	v_exp_f32_e32 v89, v89
	v_add_u32_e32 v53, s31, v244
	v_add_u32_e32 v51, s76, v245
	ds_read_b128 v[190:193], v53
	ds_read_b128 v[186:189], v53 offset:512
	s_waitcnt lgkmcnt(12)
	v_mfma_f32_32x32x16_bf16 v[2:17], v[154:157], v[114:117], v[2:17]
	v_exp_f32_e32 v90, v90
	v_exp_f32_e32 v91, v91
	v_exp_f32_e32 v92, v92
	v_exp_f32_e32 v93, v93
	ds_read_b128 v[182:185], v53 offset:2048
	ds_read_b128 v[178:181], v53 offset:2560
	s_waitcnt lgkmcnt(12)
	v_mfma_f32_32x32x16_bf16 v[18:33], v[154:157], v[118:121], v[18:33]
	v_exp_f32_e32 v94, v94
	v_exp_f32_e32 v95, v95
	v_exp_f32_e32 v96, v96
	v_exp_f32_e32 v97, v97
	ds_read_b128 v[174:177], v53 offset:4096
	ds_read_b128 v[170:173], v53 offset:4608
	s_waitcnt lgkmcnt(12)
	v_mfma_f32_32x32x16_bf16 v[2:17], v[146:149], v[122:125], v[2:17]
	v_exp_f32_e32 v66, v66
	v_exp_f32_e32 v67, v67
	v_exp_f32_e32 v68, v68
	v_exp_f32_e32 v69, v69
	ds_read_b128 v[166:169], v53 offset:6144
	ds_read_b128 v[162:165], v53 offset:6656
	s_waitcnt lgkmcnt(12)
	v_mfma_f32_32x32x16_bf16 v[18:33], v[146:149], v[98:101], v[18:33]
	v_exp_f32_e32 v70, v70
	v_exp_f32_e32 v71, v71
	v_exp_f32_e32 v72, v72
	v_exp_f32_e32 v73, v73
	s_waitcnt lgkmcnt(10)
	v_mfma_f32_32x32x16_bf16 v[2:17], v[142:145], v[102:105], v[2:17]
	v_exp_f32_e32 v74, v74
	v_exp_f32_e32 v75, v75
	v_exp_f32_e32 v76, v76
	v_exp_f32_e32 v77, v77
	s_waitcnt lgkmcnt(8)
	v_mfma_f32_32x32x16_bf16 v[18:33], v[142:145], v[106:109], v[18:33]
	v_exp_f32_e32 v78, v78
	v_exp_f32_e32 v79, v79
	v_exp_f32_e32 v80, v80
	v_exp_f32_e32 v81, v81
	s_add_i32 s6, s31, 0x2000
	s_waitcnt vmcnt(2) lgkmcnt(0)
	s_barrier
	s_cmpk_lg_i32 s31, 0x4000
	s_mov_b32 s24, s76
	s_cselect_b32 s76, s6, 0
	s_add_i32 s26, s26, 2
	s_cmp_ge_i32 s26, s91
	s_cbranch_scc0 .LBB0_618
	v_add_f32_e32 v50, v50, v194
	v_add_f32_e32 v50, v50, v195
	v_add_f32_e32 v50, v50, v196
	s_add_i32 s5, s5, -3
	s_branch .LBB0_621
